# GLA prep: slr load overlapped with the q/k/w loads (write+barrier moved after load issue)
# baseline (speedup 1.0000x reference)
; DI int otid() { int t = threadIdx.x; asm volatile("" : "+v"(t)); return t; }
; DI void gla_prep_item(const P& p, int l, int item, unsigned char* smem) {
;     const int c = item % 72, bd = item / 72, dir = bd & 1, b = bd >> 1;
;     float* slr = (float*)smem;
;     float* stot = slr + 512;
;     float* slast = stot + 256;
;     bf16_t* sq = (bf16_t*)(slast + 256);
;     bf16_t* sk = sq + 4 * 32 * 72;
;     const bf16_t* S = (const bf16_t*)(p.ws + WS_SBUF);
;     bf16_t* QT = (bf16_t*)(p.ws + WS_GLA_QT); bf16_t* KO = (bf16_t*)(p.ws + WS_GLA_KO); bf16_t* AT = (bf16_t*)(p.ws + WS_GLA_AT); float* DC = (float*)(p.ws + WS_GLA_DC);
;     const int tid = otid();
;     { const int i = tid >> 4, r = tid & 15; slr[i * 16 + r] = ((const float*)(p.ws + WS_G))[(size_t)prow(b, dir, 32 * c + i) * NNAR + G_LR + 16 * dir + r]; }
;     __syncthreads();
;     const int cch = tid & 255, half = tid >> 8, h = cch >> 6, d = cch & 63;
;     bf16_t qraw[16], kraw[16];
; #pragma unroll
;     for (int ii = 0; ii < 16; ++ii) { const size_t row = (size_t)prow(b, dir, 32 * c + 16 * half + ii); qraw[ii] = S[row * NP + C_GLA_Q + cch]; kraw[ii] = S[row * NP + C_GLA_K + cch]; }
;     float wd[16];
; #pragma unroll
;     for (int r = 0; r < 16; ++r) wd[r] = p.gla_wd[((size_t)(l * 2 + dir) * 16 + r) * 256 + cch];
.LBB0_253:
	s_andn2_b64 vcc, exec, s[0:1]
	s_cbranch_vccnz .LBB0_265
	s_add_i32 s0, s28, 0xfdc0
	s_and_b32 s1, s0, 0xffff
	s_mul_i32 s1, s1, 0xe38f
	s_lshr_b32 s2, s1, 22
	s_mul_i32 s3, s2, 0x48
	s_sub_i32 s0, s0, s3
	s_and_b32 s21, s0, 0xffff
	v_mov_b32_e32 v24, v166
	s_lshl_b32 s38, s21, 5
	s_movk_i32 s0, 0xff
	v_ashrrev_i32_e32 v0, 4, v24
	v_add_u32_e32 v0, s38, v0
	s_lshr_b32 s22, s1, 23
	v_cmp_lt_i32_e32 vcc, s0, v0
	s_and_saveexec_b64 s[0:1], vcc
	s_xor_b64 s[0:1], exec, s[0:1]
	s_lshl_b32 s3, s22, 8
	s_addk_i32 s3, 0x2000
	s_lshl_b32 s20, s22, 11
	v_add_u32_e32 v1, 0xffffff00, v0
	s_or_saveexec_b64 s[0:1], s[0:1]
	v_mov_b32_e32 v3, 0x8ff
	v_mov_b32_e32 v2, s20
	v_mov_b32_e32 v4, s3
	v_mov_b32_e32 v5, s20
	s_xor_b64 exec, exec, s[0:1]
	s_lshl_b32 s4, s22, 8
	s_lshl_b32 s3, s22, 11
	s_addk_i32 s4, 0x2000
	v_mov_b32_e32 v3, 0xff
	v_mov_b32_e32 v2, s4
	v_mov_b32_e32 v5, s3
	v_mov_b32_e32 v1, v0
	v_mov_b32_e32 v4, s4
	s_or_b64 exec, exec, s[0:1]
	s_and_b32 s24, s2, 1
	s_lshl_b32 s0, s24, 6
	s_add_u32 s0, s42, s0
	s_addc_u32 s1, s43, 0
	s_add_u32 s0, s0, 0x17ead200
	s_addc_u32 s1, s1, 0
	s_cmp_eq_u32 s24, 0
	s_cselect_b64 vcc, -1, 0
	v_sub_u32_e32 v0, v3, v0
	v_cndmask_b32_e32 v0, v0, v1, vcc
	v_and_b32_e32 v25, 15, v24
	v_add_u32_e32 v2, v0, v2
	v_mov_b64_e32 v[0:1], s[0:1]
	s_movk_i32 s0, 0xc0
	v_mad_i64_i32 v[0:1], s[0:1], v2, s0, v[0:1]
	v_lshlrev_b32_e32 v132, 2, v25
	v_lshl_add_u64 v[0:1], v[0:1], 0, v[132:133]
	global_load_dword v13, v[0:1], off
	v_lshlrev_b32_e32 v43, 2, v24
	v_add_u32_e32 v14, s26, v43
	v_ashrrev_i32_e32 v37, 8, v24
	v_readlane_b32 s2, v252, 11
	v_lshlrev_b32_e32 v26, 4, v37
	s_or_b32 s2, s24, s2
	s_mov_b64 s[0:1], 0x6c3c000
	s_movk_i32 s5, 0x100
	s_ashr_i32 s3, s2, 31
	s_lshl_b64 s[2:3], s[2:3], 14
	v_readlane_b32 s48, v254, 39
	v_readlane_b32 s49, v254, 40
	s_add_u32 s36, s48, s2
	s_addc_u32 s37, s49, s3
	s_lshl_b32 s2, s24, 8
	v_readlane_b32 s3, v252, 12
	s_or_b32 s2, s2, s3
	s_movk_i32 s3, 0x3800
	v_readlane_b32 s50, v254, 41
	v_readlane_b32 s51, v254, 42
	s_mov_b32 s4, 0x7f800000
	v_readlane_b32 s52, v254, 43
	v_readlane_b32 s53, v254, 44
	v_readlane_b32 s54, v254, 45
	v_readlane_b32 s55, v254, 46
	v_readlane_b32 s56, v254, 47
	v_readlane_b32 s57, v254, 48
	v_readlane_b32 s58, v254, 49
	v_readlane_b32 s59, v254, 50
	v_readlane_b32 s60, v254, 51
	v_readlane_b32 s61, v254, 52
	v_readlane_b32 s62, v254, 53
	v_readlane_b32 s63, v254, 54
	v_and_b32_e32 v1, 0xff, v24
	v_lshlrev_b32_e32 v132, 1, v1
	v_add_u32_e32 v0, s38, v26
	v_lshl_add_u64 v[2:3], s[42:43], 0, v[132:133]
	v_lshl_add_u64 v[2:3], v[2:3], 0, s[0:1]
	v_cmp_gt_i32_e64 s[0:1], s5, v0
	v_add_u32_e32 v6, 0xffffff00, v0
	s_waitcnt lgkmcnt(0)
	v_cndmask_b32_e64 v7, v174, v175, s[0:1]
	v_cndmask_b32_e64 v6, v6, v0, s[0:1]
	v_sub_u32_e32 v7, v7, v0
	v_cndmask_b32_e64 v8, v5, v4, s[0:1]
	v_cndmask_b32_e32 v6, v7, v6, vcc
	v_add_u32_e32 v6, v8, v6
	v_mad_i64_i32 v[6:7], s[0:1], v6, s3, v[2:3]
	global_load_ushort v29, v[6:7], off
	global_load_ushort v27, v[6:7], off offset:512
	v_or_b32_e32 v6, 1, v0
	v_cmp_gt_i32_e64 s[0:1], s5, v6
	v_add_u32_e32 v7, 0xffffff01, v0
	v_lshlrev_b32_e32 v132, 2, v1
	v_cndmask_b32_e64 v8, v174, v175, s[0:1]
	v_cndmask_b32_e64 v7, v7, v6, s[0:1]
	v_sub_u32_e32 v6, v8, v6
	v_cndmask_b32_e64 v9, v5, v4, s[0:1]
	v_cndmask_b32_e32 v6, v6, v7, vcc
	v_add_u32_e32 v6, v9, v6
	v_mad_i64_i32 v[6:7], s[0:1], v6, s3, v[2:3]
	global_load_ushort v30, v[6:7], off
	global_load_ushort v28, v[6:7], off offset:512
	v_or_b32_e32 v6, 2, v0
	v_cmp_gt_i32_e64 s[0:1], s5, v6
	v_add_u32_e32 v7, 0xffffff02, v0
	s_nop 0
	v_cndmask_b32_e64 v8, v174, v175, s[0:1]
	v_cndmask_b32_e64 v7, v7, v6, s[0:1]
	v_sub_u32_e32 v6, v8, v6
	v_cndmask_b32_e64 v9, v5, v4, s[0:1]
	v_cndmask_b32_e32 v6, v6, v7, vcc
	v_add_u32_e32 v6, v9, v6
	v_mad_i64_i32 v[6:7], s[0:1], v6, s3, v[2:3]
	global_load_ushort v32, v[6:7], off
	global_load_ushort v31, v[6:7], off offset:512
	v_or_b32_e32 v6, 3, v0
	v_cmp_gt_i32_e64 s[0:1], s5, v6
	v_add_u32_e32 v7, 0xffffff03, v0
	s_nop 0
	v_cndmask_b32_e64 v8, v174, v175, s[0:1]
	v_cndmask_b32_e64 v7, v7, v6, s[0:1]
	v_sub_u32_e32 v6, v8, v6
	v_cndmask_b32_e64 v9, v5, v4, s[0:1]
	v_cndmask_b32_e32 v6, v6, v7, vcc
	v_add_u32_e32 v6, v9, v6
	v_mad_i64_i32 v[6:7], s[0:1], v6, s3, v[2:3]
	global_load_ushort v34, v[6:7], off
	global_load_ushort v33, v[6:7], off offset:512
	v_or_b32_e32 v6, 4, v0
	v_cmp_gt_i32_e64 s[0:1], s5, v6
	v_add_u32_e32 v7, 0xffffff04, v0
	s_nop 0
	v_cndmask_b32_e64 v8, v174, v175, s[0:1]
	v_cndmask_b32_e64 v7, v7, v6, s[0:1]
	v_sub_u32_e32 v6, v8, v6
	v_cndmask_b32_e64 v9, v5, v4, s[0:1]
	v_cndmask_b32_e32 v6, v6, v7, vcc
	v_add_u32_e32 v6, v9, v6
	v_mad_i64_i32 v[6:7], s[0:1], v6, s3, v[2:3]
	global_load_ushort v60, v[6:7], off
	global_load_ushort v59, v[6:7], off offset:512
	v_or_b32_e32 v6, 5, v0
	v_cmp_gt_i32_e64 s[0:1], s5, v6
	v_add_u32_e32 v7, 0xffffff05, v0
	s_nop 0
	v_cndmask_b32_e64 v8, v174, v175, s[0:1]
	v_cndmask_b32_e64 v7, v7, v6, s[0:1]
	v_sub_u32_e32 v6, v8, v6
	v_cndmask_b32_e64 v9, v5, v4, s[0:1]
	v_cndmask_b32_e32 v6, v6, v7, vcc
	v_add_u32_e32 v6, v9, v6
	v_mad_i64_i32 v[6:7], s[0:1], v6, s3, v[2:3]
	global_load_ushort v58, v[6:7], off
	global_load_ushort v56, v[6:7], off offset:512
	v_or_b32_e32 v6, 6, v0
	v_cmp_gt_i32_e64 s[0:1], s5, v6
	v_add_u32_e32 v7, 0xffffff06, v0
	s_nop 0
	v_cndmask_b32_e64 v8, v174, v175, s[0:1]
	v_cndmask_b32_e64 v7, v7, v6, s[0:1]
	v_sub_u32_e32 v6, v8, v6
	v_cndmask_b32_e64 v9, v5, v4, s[0:1]
	v_cndmask_b32_e32 v6, v6, v7, vcc
	v_add_u32_e32 v6, v9, v6
	v_mad_i64_i32 v[6:7], s[0:1], v6, s3, v[2:3]
	global_load_ushort v55, v[6:7], off
	global_load_ushort v53, v[6:7], off offset:512
; DI void gla_prep_item(const P& p, int l, int item, unsigned char* smem) {
;     ...
;     { const int i = tid >> 4, r = tid & 15; slr[i * 16 + r] = ((const float*)(p.ws + WS_G))[(size_t)prow(b, dir, 32 * c + i) * NNAR + G_LR + 16 * dir + r]; }
;     __syncthreads();
;     const int cch = tid & 255, half = tid >> 8, h = cch >> 6, d = cch & 63;
;     bf16_t qraw[16], kraw[16];
; #pragma unroll
;     for (int ii = 0; ii < 16; ++ii) { const size_t row = (size_t)prow(b, dir, 32 * c + 16 * half + ii); qraw[ii] = S[row * NP + C_GLA_Q + cch]; kraw[ii] = S[row * NP + C_GLA_K + cch]; }
;     float wd[16];
; #pragma unroll
;     for (int r = 0; r < 16; ++r) wd[r] = p.gla_wd[((size_t)(l * 2 + dir) * 16 + r) * 256 + cch];
;     const float bdv = p.gla_bd[(l * 2 + dir) * 256 + cch];
	v_or_b32_e32 v6, 7, v0
	v_cmp_gt_i32_e64 s[0:1], s5, v6
	v_add_u32_e32 v7, 0xffffff07, v0
	s_nop 0
	v_cndmask_b32_e64 v8, v174, v175, s[0:1]
	v_cndmask_b32_e64 v7, v7, v6, s[0:1]
	v_sub_u32_e32 v6, v8, v6
	v_cndmask_b32_e64 v9, v5, v4, s[0:1]
	v_cndmask_b32_e32 v6, v6, v7, vcc
	v_add_u32_e32 v6, v9, v6
	v_mad_i64_i32 v[6:7], s[0:1], v6, s3, v[2:3]
	global_load_ushort v57, v[6:7], off
	global_load_ushort v54, v[6:7], off offset:512
	v_or_b32_e32 v6, 8, v0
	v_cmp_gt_i32_e64 s[0:1], s5, v6
	v_add_u32_e32 v7, 0xffffff08, v0
	s_nop 0
	v_cndmask_b32_e64 v8, v174, v175, s[0:1]
	v_cndmask_b32_e64 v7, v7, v6, s[0:1]
	v_sub_u32_e32 v6, v8, v6
	v_cndmask_b32_e64 v9, v5, v4, s[0:1]
	v_cndmask_b32_e32 v6, v6, v7, vcc
	v_add_u32_e32 v6, v9, v6
	v_mad_i64_i32 v[6:7], s[0:1], v6, s3, v[2:3]
	global_load_ushort v52, v[6:7], off
	global_load_ushort v51, v[6:7], off offset:512
	v_or_b32_e32 v6, 9, v0
	v_cmp_gt_i32_e64 s[0:1], s5, v6
	v_add_u32_e32 v7, 0xffffff09, v0
	s_nop 0
	v_cndmask_b32_e64 v8, v174, v175, s[0:1]
	v_cndmask_b32_e64 v7, v7, v6, s[0:1]
	v_sub_u32_e32 v6, v8, v6
	v_cndmask_b32_e64 v9, v5, v4, s[0:1]
	v_cndmask_b32_e32 v6, v6, v7, vcc
	v_add_u32_e32 v6, v9, v6
	v_mad_i64_i32 v[6:7], s[0:1], v6, s3, v[2:3]
	global_load_ushort v50, v[6:7], off
	global_load_ushort v49, v[6:7], off offset:512
	v_or_b32_e32 v6, 10, v0
	v_cmp_gt_i32_e64 s[0:1], s5, v6
	v_add_u32_e32 v7, 0xffffff0a, v0
	s_nop 0
	v_cndmask_b32_e64 v8, v174, v175, s[0:1]
	v_cndmask_b32_e64 v7, v7, v6, s[0:1]
	v_sub_u32_e32 v6, v8, v6
	v_cndmask_b32_e64 v9, v5, v4, s[0:1]
	v_cndmask_b32_e32 v6, v6, v7, vcc
	v_add_u32_e32 v6, v9, v6
	v_mad_i64_i32 v[6:7], s[0:1], v6, s3, v[2:3]
	global_load_ushort v48, v[6:7], off
	global_load_ushort v47, v[6:7], off offset:512
	v_or_b32_e32 v6, 11, v0
	v_cmp_gt_i32_e64 s[0:1], s5, v6
	v_add_u32_e32 v7, 0xffffff0b, v0
	s_nop 0
	v_cndmask_b32_e64 v8, v174, v175, s[0:1]
	v_cndmask_b32_e64 v7, v7, v6, s[0:1]
	v_sub_u32_e32 v6, v8, v6
	v_cndmask_b32_e64 v9, v5, v4, s[0:1]
	v_cndmask_b32_e32 v6, v6, v7, vcc
	v_add_u32_e32 v6, v9, v6
	v_mad_i64_i32 v[6:7], s[0:1], v6, s3, v[2:3]
	global_load_ushort v46, v[6:7], off
	global_load_ushort v45, v[6:7], off offset:512
	v_or_b32_e32 v6, 12, v0
	v_cmp_gt_i32_e64 s[0:1], s5, v6
	v_add_u32_e32 v7, 0xffffff0c, v0
	s_nop 0
	v_cndmask_b32_e64 v8, v174, v175, s[0:1]
	v_cndmask_b32_e64 v7, v7, v6, s[0:1]
	v_sub_u32_e32 v6, v8, v6
	v_cndmask_b32_e64 v9, v5, v4, s[0:1]
	v_cndmask_b32_e32 v6, v6, v7, vcc
	v_add_u32_e32 v6, v9, v6
	v_mad_i64_i32 v[6:7], s[0:1], v6, s3, v[2:3]
	global_load_ushort v44, v[6:7], off
	global_load_ushort v42, v[6:7], off offset:512
	v_or_b32_e32 v6, 13, v0
	v_cmp_gt_i32_e64 s[0:1], s5, v6
	v_add_u32_e32 v7, 0xffffff0d, v0
	s_nop 0
	v_cndmask_b32_e64 v8, v174, v175, s[0:1]
	v_cndmask_b32_e64 v7, v7, v6, s[0:1]
	v_sub_u32_e32 v6, v8, v6
	v_cndmask_b32_e64 v9, v5, v4, s[0:1]
	v_cndmask_b32_e32 v6, v6, v7, vcc
	v_add_u32_e32 v6, v9, v6
	v_mad_i64_i32 v[6:7], s[0:1], v6, s3, v[2:3]
	global_load_ushort v41, v[6:7], off
	global_load_ushort v40, v[6:7], off offset:512
	v_or_b32_e32 v6, 14, v0
	v_cmp_gt_i32_e64 s[0:1], s5, v6
	v_add_u32_e32 v7, 0xffffff0e, v0
	s_nop 0
	v_cndmask_b32_e64 v8, v174, v175, s[0:1]
	v_cndmask_b32_e64 v7, v7, v6, s[0:1]
	v_sub_u32_e32 v6, v8, v6
	v_cndmask_b32_e64 v9, v5, v4, s[0:1]
	v_cndmask_b32_e32 v6, v6, v7, vcc
	v_add_u32_e32 v6, v9, v6
	v_mad_i64_i32 v[6:7], s[0:1], v6, s3, v[2:3]
	global_load_ushort v39, v[6:7], off
	global_load_ushort v38, v[6:7], off offset:512
	v_or_b32_e32 v6, 15, v0
	v_cmp_gt_i32_e64 s[0:1], s5, v6
	v_add_u32_e32 v7, 0xffffff0f, v0
	s_nop 0
	v_cndmask_b32_e64 v8, v174, v175, s[0:1]
	v_cndmask_b32_e64 v7, v7, v6, s[0:1]
	v_cndmask_b32_e64 v4, v5, v4, s[0:1]
	v_sub_u32_e32 v5, v8, v6
	v_cndmask_b32_e32 v5, v5, v7, vcc
	v_add_u32_e32 v4, v4, v5
	v_mad_i64_i32 v[2:3], s[0:1], v4, s3, v[2:3]
	global_load_ushort v36, v[2:3], off
	global_load_ushort v35, v[2:3], off offset:512
	v_lshl_add_u64 v[2:3], s[36:37], 0, v[132:133]
	s_movk_i32 s0, 0x1000
	v_add_co_u32_e32 v4, vcc, s0, v2
	s_movk_i32 s0, 0x3000
	s_nop 0
	v_addc_co_u32_e32 v5, vcc, 0, v3, vcc
	v_add_co_u32_e32 v10, vcc, s33, v2
	global_load_dword v67, v132, s[36:37]
	global_load_dword v68, v132, s[36:37] offset:1024
	global_load_dword v63, v132, s[36:37] offset:2048
	global_load_dword v64, v132, s[36:37] offset:3072
	v_addc_co_u32_e32 v11, vcc, 0, v3, vcc
	global_load_dword v65, v[10:11], off offset:-4096
	global_load_dword v66, v[4:5], off offset:1024
	global_load_dword v61, v[4:5], off offset:2048
	global_load_dword v62, v[4:5], off offset:3072
	global_load_dword v8, v[10:11], off
	global_load_dword v9, v[10:11], off offset:1024
	global_load_dword v6, v[10:11], off offset:2048
	global_load_dword v7, v[10:11], off offset:3072
	v_add_co_u32_e32 v10, vcc, s0, v2
	s_mov_b32 s3, 0x3f317217
	s_nop 0
	v_addc_co_u32_e32 v11, vcc, 0, v3, vcc
	global_load_dword v4, v[10:11], off
	global_load_dword v5, v[10:11], off offset:1024
	global_load_dword v2, v[10:11], off offset:2048
	global_load_dword v3, v[10:11], off offset:3072
	v_or_b32_e32 v10, s2, v1
	v_ashrrev_i32_e32 v11, 31, v10
	v_lshl_add_u64 v[10:11], v[10:11], 2, s[50:51]
	global_load_dword v69, v[10:11], off
	v_and_b32_e32 v10, 0x3fffff00, v24
	v_lshl_add_u32 v70, v10, 2, s26
	s_waitcnt vmcnt(49)
	ds_write_b32 v14, v13
	s_waitcnt lgkmcnt(0)
	s_barrier
; DI void gla_prep_item(const P& p, int l, int item, unsigned char* smem) {
;     ...
;     float cum[16]; float run = 0.f;
; #pragma unroll
;     for (int ii = 0; ii < 16; ++ii) {
;         const int i = 16 * half + ii; float z = bdv;
; #pragma unroll
;         for (int r = 0; r < 16; ++r) z += slr[i * 16 + r] * wd[r];
;         const float ls = fminf(z, 0.f) - __logf(1.f + __expf(-fabsf(z)));
;         run += ls * (1.f / 16.f); cum[ii] = run;
;     }
	ds_read2_b32 v[10:11], v70 offset1:1
	s_mov_b32 s2, 0xbfb8aa3b
	s_waitcnt vmcnt(0) lgkmcnt(0)
	v_fma_f32 v12, v67, v10, v69
	v_fmac_f32_e32 v12, v68, v11
	ds_read2_b32 v[10:11], v70 offset0:2 offset1:3
	s_waitcnt lgkmcnt(0)
	v_fmac_f32_e32 v12, v63, v10
	v_fmac_f32_e32 v12, v64, v11
	ds_read2_b32 v[10:11], v70 offset0:4 offset1:5
	s_waitcnt lgkmcnt(0)
	v_fmac_f32_e32 v12, v65, v10
	v_fmac_f32_e32 v12, v66, v11
	ds_read2_b32 v[10:11], v70 offset0:6 offset1:7
	s_waitcnt lgkmcnt(0)
	v_fmac_f32_e32 v12, v61, v10
	v_fmac_f32_e32 v12, v62, v11
	ds_read2_b32 v[10:11], v70 offset0:8 offset1:9
	s_waitcnt lgkmcnt(0)
	v_pk_mul_f32 v[10:11], v[8:9], v[10:11]
	s_nop 0
	v_add_f32_e32 v10, v12, v10
	v_add_f32_e32 v12, v10, v11
	ds_read2_b32 v[10:11], v70 offset0:10 offset1:11
	s_waitcnt lgkmcnt(0)
	v_pk_mul_f32 v[10:11], v[6:7], v[10:11]
	s_nop 0
	v_add_f32_e32 v10, v12, v10
	v_add_f32_e32 v12, v10, v11
	ds_read2_b32 v[10:11], v70 offset0:12 offset1:13
	s_waitcnt lgkmcnt(0)
	v_pk_mul_f32 v[10:11], v[4:5], v[10:11]
	s_nop 0
	v_add_f32_e32 v10, v12, v10
	v_add_f32_e32 v12, v10, v11
	ds_read2_b32 v[10:11], v70 offset0:14 offset1:15
	s_waitcnt lgkmcnt(0)
	v_pk_mul_f32 v[10:11], v[2:3], v[10:11]
	s_nop 0
	v_add_f32_e32 v10, v12, v10
	v_add_f32_e32 v10, v10, v11
	v_min_f32_e32 v11, 0, v10
	v_mul_f32_e64 v10, |v10|, s2
	v_exp_f32_e32 v10, v10
	s_nop 0
	v_add_f32_e32 v10, 1.0, v10
	v_cmp_gt_f32_e32 vcc, s23, v10
	s_nop 1
	v_cndmask_b32_e64 v12, 0, 32, vcc
	v_ldexp_f32 v10, v10, v12
	v_log_f32_e32 v10, v10
	s_nop 0
	v_mul_f32_e32 v12, 0x3f317217, v10
	v_fma_f32 v12, v10, s3, -v12
	v_fmac_f32_e32 v12, 0x3377d1cf, v10
	v_fmac_f32_e32 v12, 0x3f317217, v10
	v_cmp_lt_f32_e64 s[0:1], |v10|, s4
	s_nop 1
	v_cndmask_b32_e64 v10, v10, v12, s[0:1]
	v_cndmask_b32_e32 v12, 0, v176, vcc
	v_sub_f32_e32 v10, v10, v12
	v_sub_f32_e32 v12, v11, v10
	ds_read2_b32 v[10:11], v70 offset0:16 offset1:17
	s_waitcnt lgkmcnt(0)
	v_fma_f32 v13, v67, v10, v69
	v_fmac_f32_e32 v13, v68, v11
	ds_read2_b32 v[10:11], v70 offset0:18 offset1:19
	s_waitcnt lgkmcnt(0)
	v_fmac_f32_e32 v13, v63, v10
	v_fmac_f32_e32 v13, v64, v11
	ds_read2_b32 v[10:11], v70 offset0:20 offset1:21
	s_waitcnt lgkmcnt(0)
	v_fmac_f32_e32 v13, v65, v10
	v_fmac_f32_e32 v13, v66, v11
	ds_read2_b32 v[10:11], v70 offset0:22 offset1:23
	s_waitcnt lgkmcnt(0)
	v_fmac_f32_e32 v13, v61, v10
	v_fmac_f32_e32 v13, v62, v11
	ds_read2_b32 v[10:11], v70 offset0:24 offset1:25
	s_waitcnt lgkmcnt(0)
	v_pk_mul_f32 v[10:11], v[8:9], v[10:11]
	s_nop 0
	v_add_f32_e32 v10, v13, v10
	v_add_f32_e32 v13, v10, v11
	ds_read2_b32 v[10:11], v70 offset0:26 offset1:27
	s_waitcnt lgkmcnt(0)
	v_pk_mul_f32 v[10:11], v[6:7], v[10:11]
	s_nop 0
	v_add_f32_e32 v10, v13, v10
	v_add_f32_e32 v13, v10, v11
	ds_read2_b32 v[10:11], v70 offset0:28 offset1:29
	s_waitcnt lgkmcnt(0)
	v_pk_mul_f32 v[10:11], v[4:5], v[10:11]
	s_nop 0
	v_add_f32_e32 v10, v13, v10
	v_add_f32_e32 v13, v10, v11
	ds_read2_b32 v[10:11], v70 offset0:30 offset1:31
	s_waitcnt lgkmcnt(0)
	v_pk_mul_f32 v[10:11], v[2:3], v[10:11]
	s_nop 0
	v_add_f32_e32 v10, v13, v10
	v_add_f32_e32 v10, v10, v11
	v_min_f32_e32 v11, 0, v10
	v_mul_f32_e64 v10, |v10|, s2
	v_exp_f32_e32 v10, v10
	s_nop 0
	v_add_f32_e32 v10, 1.0, v10
	v_cmp_gt_f32_e32 vcc, s23, v10
	s_nop 1
	v_cndmask_b32_e64 v13, 0, 32, vcc
	v_ldexp_f32 v10, v10, v13
	v_log_f32_e32 v10, v10
	s_nop 0
	v_mul_f32_e32 v13, 0x3f317217, v10
	v_fma_f32 v13, v10, s3, -v13
	v_fmac_f32_e32 v13, 0x3377d1cf, v10
	v_fmac_f32_e32 v13, 0x3f317217, v10
	v_cmp_lt_f32_e64 s[0:1], |v10|, s4
	s_nop 1
	v_cndmask_b32_e64 v10, v10, v13, s[0:1]
	v_cndmask_b32_e32 v13, 0, v176, vcc
	v_sub_f32_e32 v10, v10, v13
	s_mov_b32 s0, 0x3d800000
	v_sub_f32_e32 v11, v11, v10
	v_fma_f32 v10, v12, s0, 0
	ds_read2_b32 v[12:13], v70 offset0:32 offset1:33
	v_fmamk_f32 v11, v11, 0x3d800000, v10
	s_waitcnt lgkmcnt(0)
	v_fma_f32 v14, v67, v12, v69
	v_fmac_f32_e32 v14, v68, v13
	ds_read2_b32 v[12:13], v70 offset0:34 offset1:35
	s_waitcnt lgkmcnt(0)
	v_fmac_f32_e32 v14, v63, v12
	v_fmac_f32_e32 v14, v64, v13
	ds_read2_b32 v[12:13], v70 offset0:36 offset1:37
	s_waitcnt lgkmcnt(0)
	v_fmac_f32_e32 v14, v65, v12
	v_fmac_f32_e32 v14, v66, v13
	ds_read2_b32 v[12:13], v70 offset0:38 offset1:39
	s_waitcnt lgkmcnt(0)
	v_fmac_f32_e32 v14, v61, v12
	v_fmac_f32_e32 v14, v62, v13
	ds_read2_b32 v[12:13], v70 offset0:40 offset1:41
	s_waitcnt lgkmcnt(0)
	v_pk_mul_f32 v[12:13], v[8:9], v[12:13]
	s_nop 0
	v_add_f32_e32 v12, v14, v12
	v_add_f32_e32 v14, v12, v13
	ds_read2_b32 v[12:13], v70 offset0:42 offset1:43
	s_waitcnt lgkmcnt(0)
	v_pk_mul_f32 v[12:13], v[6:7], v[12:13]
	s_nop 0
	v_add_f32_e32 v12, v14, v12
	v_add_f32_e32 v14, v12, v13
	ds_read2_b32 v[12:13], v70 offset0:44 offset1:45
	s_waitcnt lgkmcnt(0)
	v_pk_mul_f32 v[12:13], v[4:5], v[12:13]
	s_nop 0
	v_add_f32_e32 v12, v14, v12
	v_add_f32_e32 v14, v12, v13
	ds_read2_b32 v[12:13], v70 offset0:46 offset1:47
	s_waitcnt lgkmcnt(0)
	v_pk_mul_f32 v[12:13], v[2:3], v[12:13]
	s_nop 0
	v_add_f32_e32 v12, v14, v12
	v_add_f32_e32 v12, v12, v13
	v_min_f32_e32 v13, 0, v12
	v_mul_f32_e64 v12, |v12|, s2
	v_exp_f32_e32 v12, v12
	s_nop 0
	v_add_f32_e32 v12, 1.0, v12
	v_cmp_gt_f32_e32 vcc, s23, v12
	s_nop 1
	v_cndmask_b32_e64 v14, 0, 32, vcc
	v_ldexp_f32 v12, v12, v14
	v_log_f32_e32 v12, v12
	s_nop 0
	v_mul_f32_e32 v14, 0x3f317217, v12
	v_fma_f32 v14, v12, s3, -v14
	v_fmac_f32_e32 v14, 0x3377d1cf, v12
	v_fmac_f32_e32 v14, 0x3f317217, v12
	v_cmp_lt_f32_e64 s[0:1], |v12|, s4
	s_nop 1
	v_cndmask_b32_e64 v12, v12, v14, s[0:1]
	v_cndmask_b32_e32 v14, 0, v176, vcc
	v_sub_f32_e32 v12, v12, v14
	v_sub_f32_e32 v14, v13, v12
	ds_read2_b32 v[12:13], v70 offset0:48 offset1:49
	s_waitcnt lgkmcnt(0)
; DI void gla_prep_item(const P& p, int l, int item, unsigned char* smem) {
;     ...
;     float cum[16]; float run = 0.f;
; #pragma unroll
;     for (int ii = 0; ii < 16; ++ii) {
;         const int i = 16 * half + ii; float z = bdv;
; #pragma unroll
;         for (int r = 0; r < 16; ++r) z += slr[i * 16 + r] * wd[r];
;         const float ls = fminf(z, 0.f) - __logf(1.f + __expf(-fabsf(z)));
;         run += ls * (1.f / 16.f); cum[ii] = run;
;     }
	v_fma_f32 v15, v67, v12, v69
	v_fmac_f32_e32 v15, v68, v13
	ds_read2_b32 v[12:13], v70 offset0:50 offset1:51
	s_waitcnt lgkmcnt(0)
	v_fmac_f32_e32 v15, v63, v12
	v_fmac_f32_e32 v15, v64, v13
	ds_read2_b32 v[12:13], v70 offset0:52 offset1:53
	s_waitcnt lgkmcnt(0)
	v_fmac_f32_e32 v15, v65, v12
	v_fmac_f32_e32 v15, v66, v13
	ds_read2_b32 v[12:13], v70 offset0:54 offset1:55
	s_waitcnt lgkmcnt(0)
	v_fmac_f32_e32 v15, v61, v12
	v_fmac_f32_e32 v15, v62, v13
	ds_read2_b32 v[12:13], v70 offset0:56 offset1:57
	s_waitcnt lgkmcnt(0)
	v_pk_mul_f32 v[12:13], v[8:9], v[12:13]
	s_nop 0
	v_add_f32_e32 v12, v15, v12
	v_add_f32_e32 v15, v12, v13
	ds_read2_b32 v[12:13], v70 offset0:58 offset1:59
	s_waitcnt lgkmcnt(0)
	v_pk_mul_f32 v[12:13], v[6:7], v[12:13]
	s_nop 0
	v_add_f32_e32 v12, v15, v12
	v_add_f32_e32 v15, v12, v13
	ds_read2_b32 v[12:13], v70 offset0:60 offset1:61
	s_waitcnt lgkmcnt(0)
	v_pk_mul_f32 v[12:13], v[4:5], v[12:13]
	s_nop 0
	v_add_f32_e32 v12, v15, v12
	v_add_f32_e32 v15, v12, v13
	ds_read2_b32 v[12:13], v70 offset0:62 offset1:63
	s_waitcnt lgkmcnt(0)
	v_pk_mul_f32 v[12:13], v[2:3], v[12:13]
	s_nop 0
	v_add_f32_e32 v12, v15, v12
	v_add_f32_e32 v12, v12, v13
	v_min_f32_e32 v13, 0, v12
	v_mul_f32_e64 v12, |v12|, s2
	v_exp_f32_e32 v12, v12
	s_nop 0
	v_add_f32_e32 v12, 1.0, v12
	v_cmp_gt_f32_e32 vcc, s23, v12
	s_nop 1
	v_cndmask_b32_e64 v15, 0, 32, vcc
	v_ldexp_f32 v12, v12, v15
	v_log_f32_e32 v12, v12
	s_nop 0
	v_mul_f32_e32 v15, 0x3f317217, v12
	v_fma_f32 v15, v12, s3, -v15
	v_fmac_f32_e32 v15, 0x3377d1cf, v12
	v_fmac_f32_e32 v15, 0x3f317217, v12
	v_cmp_lt_f32_e64 s[0:1], |v12|, s4
	s_nop 1
	v_cndmask_b32_e64 v12, v12, v15, s[0:1]
	v_cndmask_b32_e32 v15, 0, v176, vcc
	v_sub_f32_e32 v12, v12, v15
	v_sub_f32_e32 v13, v13, v12
	v_fmamk_f32 v12, v14, 0x3d800000, v11
	ds_read2_b32 v[14:15], v70 offset0:64 offset1:65
	v_fmamk_f32 v13, v13, 0x3d800000, v12
	s_waitcnt lgkmcnt(0)
	v_fma_f32 v16, v67, v14, v69
	v_fmac_f32_e32 v16, v68, v15
	ds_read2_b32 v[14:15], v70 offset0:66 offset1:67
	s_waitcnt lgkmcnt(0)
	v_fmac_f32_e32 v16, v63, v14
	v_fmac_f32_e32 v16, v64, v15
	ds_read2_b32 v[14:15], v70 offset0:68 offset1:69
	s_waitcnt lgkmcnt(0)
	v_fmac_f32_e32 v16, v65, v14
	v_fmac_f32_e32 v16, v66, v15
	ds_read2_b32 v[14:15], v70 offset0:70 offset1:71
	s_waitcnt lgkmcnt(0)
	v_fmac_f32_e32 v16, v61, v14
	v_fmac_f32_e32 v16, v62, v15
	ds_read2_b32 v[14:15], v70 offset0:72 offset1:73
	s_waitcnt lgkmcnt(0)
	v_pk_mul_f32 v[14:15], v[8:9], v[14:15]
	s_nop 0
	v_add_f32_e32 v14, v16, v14
	v_add_f32_e32 v16, v14, v15
	ds_read2_b32 v[14:15], v70 offset0:74 offset1:75
	s_waitcnt lgkmcnt(0)
	v_pk_mul_f32 v[14:15], v[6:7], v[14:15]
	s_nop 0
	v_add_f32_e32 v14, v16, v14
	v_add_f32_e32 v16, v14, v15
	ds_read2_b32 v[14:15], v70 offset0:76 offset1:77
	s_waitcnt lgkmcnt(0)
	v_pk_mul_f32 v[14:15], v[4:5], v[14:15]
	s_nop 0
	v_add_f32_e32 v14, v16, v14
	v_add_f32_e32 v16, v14, v15
	ds_read2_b32 v[14:15], v70 offset0:78 offset1:79
	s_waitcnt lgkmcnt(0)
	v_pk_mul_f32 v[14:15], v[2:3], v[14:15]
	s_nop 0
	v_add_f32_e32 v14, v16, v14
	v_add_f32_e32 v14, v14, v15
	v_min_f32_e32 v15, 0, v14
	v_mul_f32_e64 v14, |v14|, s2
	v_exp_f32_e32 v14, v14
	s_nop 0
	v_add_f32_e32 v14, 1.0, v14
	v_cmp_gt_f32_e32 vcc, s23, v14
	s_nop 1
	v_cndmask_b32_e64 v16, 0, 32, vcc
	v_ldexp_f32 v14, v14, v16
	v_log_f32_e32 v14, v14
	s_nop 0
	v_mul_f32_e32 v16, 0x3f317217, v14
	v_fma_f32 v16, v14, s3, -v16
	v_fmac_f32_e32 v16, 0x3377d1cf, v14
	v_fmac_f32_e32 v16, 0x3f317217, v14
	v_cmp_lt_f32_e64 s[0:1], |v14|, s4
	s_nop 1
	v_cndmask_b32_e64 v14, v14, v16, s[0:1]
	v_cndmask_b32_e32 v16, 0, v176, vcc
	v_sub_f32_e32 v14, v14, v16
	v_sub_f32_e32 v16, v15, v14
	ds_read2_b32 v[14:15], v70 offset0:80 offset1:81
	s_waitcnt lgkmcnt(0)
	v_fma_f32 v17, v67, v14, v69
	v_fmac_f32_e32 v17, v68, v15
	ds_read2_b32 v[14:15], v70 offset0:82 offset1:83
	s_waitcnt lgkmcnt(0)
	v_fmac_f32_e32 v17, v63, v14
	v_fmac_f32_e32 v17, v64, v15
	ds_read2_b32 v[14:15], v70 offset0:84 offset1:85
	s_waitcnt lgkmcnt(0)
	v_fmac_f32_e32 v17, v65, v14
	v_fmac_f32_e32 v17, v66, v15
	ds_read2_b32 v[14:15], v70 offset0:86 offset1:87
	s_waitcnt lgkmcnt(0)
	v_fmac_f32_e32 v17, v61, v14
	v_fmac_f32_e32 v17, v62, v15
	ds_read2_b32 v[14:15], v70 offset0:88 offset1:89
	s_waitcnt lgkmcnt(0)
	v_pk_mul_f32 v[14:15], v[8:9], v[14:15]
	s_nop 0
	v_add_f32_e32 v14, v17, v14
	v_add_f32_e32 v17, v14, v15
	ds_read2_b32 v[14:15], v70 offset0:90 offset1:91
	s_waitcnt lgkmcnt(0)
	v_pk_mul_f32 v[14:15], v[6:7], v[14:15]
	s_nop 0
	v_add_f32_e32 v14, v17, v14
	v_add_f32_e32 v17, v14, v15
	ds_read2_b32 v[14:15], v70 offset0:92 offset1:93
	s_waitcnt lgkmcnt(0)
	v_pk_mul_f32 v[14:15], v[4:5], v[14:15]
	s_nop 0
	v_add_f32_e32 v14, v17, v14
	v_add_f32_e32 v17, v14, v15
	ds_read2_b32 v[14:15], v70 offset0:94 offset1:95
	s_waitcnt lgkmcnt(0)
	v_pk_mul_f32 v[14:15], v[2:3], v[14:15]
	s_nop 0
	v_add_f32_e32 v14, v17, v14
	v_add_f32_e32 v14, v14, v15
	v_min_f32_e32 v15, 0, v14
	v_mul_f32_e64 v14, |v14|, s2
	v_exp_f32_e32 v14, v14
	s_nop 0
	v_add_f32_e32 v14, 1.0, v14
	v_cmp_gt_f32_e32 vcc, s23, v14
	s_nop 1
	v_cndmask_b32_e64 v17, 0, 32, vcc
	v_ldexp_f32 v14, v14, v17
	v_log_f32_e32 v14, v14
	s_nop 0
	v_mul_f32_e32 v17, 0x3f317217, v14
	v_fma_f32 v17, v14, s3, -v17
	v_fmac_f32_e32 v17, 0x3377d1cf, v14
	v_fmac_f32_e32 v17, 0x3f317217, v14
	v_cmp_lt_f32_e64 s[0:1], |v14|, s4
	s_nop 1
	v_cndmask_b32_e64 v14, v14, v17, s[0:1]
	v_cndmask_b32_e32 v17, 0, v176, vcc
	v_sub_f32_e32 v14, v14, v17
	v_sub_f32_e32 v15, v15, v14
	v_fmamk_f32 v14, v16, 0x3d800000, v13
	ds_read2_b32 v[16:17], v70 offset0:96 offset1:97
	v_fmamk_f32 v15, v15, 0x3d800000, v14
	s_waitcnt lgkmcnt(0)
; DI void gla_prep_item(const P& p, int l, int item, unsigned char* smem) {
;     ...
;     float cum[16]; float run = 0.f;
; #pragma unroll
;     for (int ii = 0; ii < 16; ++ii) {
;         const int i = 16 * half + ii; float z = bdv;
; #pragma unroll
;         for (int r = 0; r < 16; ++r) z += slr[i * 16 + r] * wd[r];
;         const float ls = fminf(z, 0.f) - __logf(1.f + __expf(-fabsf(z)));
;         run += ls * (1.f / 16.f); cum[ii] = run;
;     }
	v_fma_f32 v18, v67, v16, v69
	v_fmac_f32_e32 v18, v68, v17
	ds_read2_b32 v[16:17], v70 offset0:98 offset1:99
	s_waitcnt lgkmcnt(0)
	v_fmac_f32_e32 v18, v63, v16
	v_fmac_f32_e32 v18, v64, v17
	ds_read2_b32 v[16:17], v70 offset0:100 offset1:101
	s_waitcnt lgkmcnt(0)
	v_fmac_f32_e32 v18, v65, v16
	v_fmac_f32_e32 v18, v66, v17
	ds_read2_b32 v[16:17], v70 offset0:102 offset1:103
	s_waitcnt lgkmcnt(0)
	v_fmac_f32_e32 v18, v61, v16
	v_fmac_f32_e32 v18, v62, v17
	ds_read2_b32 v[16:17], v70 offset0:104 offset1:105
	s_waitcnt lgkmcnt(0)
	v_pk_mul_f32 v[16:17], v[8:9], v[16:17]
	s_nop 0
	v_add_f32_e32 v16, v18, v16
	v_add_f32_e32 v18, v16, v17
	ds_read2_b32 v[16:17], v70 offset0:106 offset1:107
	s_waitcnt lgkmcnt(0)
	v_pk_mul_f32 v[16:17], v[6:7], v[16:17]
	s_nop 0
	v_add_f32_e32 v16, v18, v16
	v_add_f32_e32 v18, v16, v17
	ds_read2_b32 v[16:17], v70 offset0:108 offset1:109
	s_waitcnt lgkmcnt(0)
	v_pk_mul_f32 v[16:17], v[4:5], v[16:17]
	s_nop 0
	v_add_f32_e32 v16, v18, v16
	v_add_f32_e32 v18, v16, v17
	ds_read2_b32 v[16:17], v70 offset0:110 offset1:111
	s_waitcnt lgkmcnt(0)
	v_pk_mul_f32 v[16:17], v[2:3], v[16:17]
	s_nop 0
	v_add_f32_e32 v16, v18, v16
	v_add_f32_e32 v16, v16, v17
	v_min_f32_e32 v17, 0, v16
	v_mul_f32_e64 v16, |v16|, s2
	v_exp_f32_e32 v16, v16
	s_nop 0
	v_add_f32_e32 v16, 1.0, v16
	v_cmp_gt_f32_e32 vcc, s23, v16
	s_nop 1
	v_cndmask_b32_e64 v18, 0, 32, vcc
	v_ldexp_f32 v16, v16, v18
	v_log_f32_e32 v16, v16
	s_nop 0
	v_mul_f32_e32 v18, 0x3f317217, v16
	v_fma_f32 v18, v16, s3, -v18
	v_fmac_f32_e32 v18, 0x3377d1cf, v16
	v_fmac_f32_e32 v18, 0x3f317217, v16
	v_cmp_lt_f32_e64 s[0:1], |v16|, s4
	s_nop 1
	v_cndmask_b32_e64 v16, v16, v18, s[0:1]
	v_cndmask_b32_e32 v18, 0, v176, vcc
	v_sub_f32_e32 v16, v16, v18
	v_sub_f32_e32 v18, v17, v16
	ds_read2_b32 v[16:17], v70 offset0:112 offset1:113
	s_waitcnt lgkmcnt(0)
	v_fma_f32 v19, v67, v16, v69
	v_fmac_f32_e32 v19, v68, v17
	ds_read2_b32 v[16:17], v70 offset0:114 offset1:115
	s_waitcnt lgkmcnt(0)
	v_fmac_f32_e32 v19, v63, v16
	v_fmac_f32_e32 v19, v64, v17
	ds_read2_b32 v[16:17], v70 offset0:116 offset1:117
	s_waitcnt lgkmcnt(0)
	v_fmac_f32_e32 v19, v65, v16
	v_fmac_f32_e32 v19, v66, v17
	ds_read2_b32 v[16:17], v70 offset0:118 offset1:119
	s_waitcnt lgkmcnt(0)
	v_fmac_f32_e32 v19, v61, v16
	v_fmac_f32_e32 v19, v62, v17
	ds_read2_b32 v[16:17], v70 offset0:120 offset1:121
	s_waitcnt lgkmcnt(0)
	v_pk_mul_f32 v[16:17], v[8:9], v[16:17]
	s_nop 0
	v_add_f32_e32 v16, v19, v16
	v_add_f32_e32 v19, v16, v17
	ds_read2_b32 v[16:17], v70 offset0:122 offset1:123
	s_waitcnt lgkmcnt(0)
	v_pk_mul_f32 v[16:17], v[6:7], v[16:17]
	s_nop 0
	v_add_f32_e32 v16, v19, v16
	v_add_f32_e32 v19, v16, v17
	ds_read2_b32 v[16:17], v70 offset0:124 offset1:125
	s_waitcnt lgkmcnt(0)
	v_pk_mul_f32 v[16:17], v[4:5], v[16:17]
	s_nop 0
	v_add_f32_e32 v16, v19, v16
	v_add_f32_e32 v19, v16, v17
	ds_read2_b32 v[16:17], v70 offset0:126 offset1:127
	s_waitcnt lgkmcnt(0)
	v_pk_mul_f32 v[16:17], v[2:3], v[16:17]
	s_nop 0
	v_add_f32_e32 v16, v19, v16
	v_add_f32_e32 v16, v16, v17
	v_min_f32_e32 v17, 0, v16
	v_mul_f32_e64 v16, |v16|, s2
	v_exp_f32_e32 v16, v16
	s_nop 0
	v_add_f32_e32 v16, 1.0, v16
	v_cmp_gt_f32_e32 vcc, s23, v16
	s_nop 1
	v_cndmask_b32_e64 v19, 0, 32, vcc
	v_ldexp_f32 v16, v16, v19
	v_log_f32_e32 v16, v16
	s_nop 0
	v_mul_f32_e32 v19, 0x3f317217, v16
	v_fma_f32 v19, v16, s3, -v19
	v_fmac_f32_e32 v19, 0x3377d1cf, v16
	v_fmac_f32_e32 v19, 0x3f317217, v16
	v_cmp_lt_f32_e64 s[0:1], |v16|, s4
	s_nop 1
	v_cndmask_b32_e64 v16, v16, v19, s[0:1]
	v_cndmask_b32_e32 v19, 0, v176, vcc
	v_sub_f32_e32 v16, v16, v19
	v_sub_f32_e32 v17, v17, v16
	v_fmamk_f32 v16, v18, 0x3d800000, v15
	ds_read2_b32 v[18:19], v70 offset0:128 offset1:129
	v_fmamk_f32 v17, v17, 0x3d800000, v16
	s_waitcnt lgkmcnt(0)
	v_fma_f32 v20, v67, v18, v69
	v_fmac_f32_e32 v20, v68, v19
	ds_read2_b32 v[18:19], v70 offset0:130 offset1:131
	s_waitcnt lgkmcnt(0)
	v_fmac_f32_e32 v20, v63, v18
	v_fmac_f32_e32 v20, v64, v19
	ds_read2_b32 v[18:19], v70 offset0:132 offset1:133
	s_waitcnt lgkmcnt(0)
	v_fmac_f32_e32 v20, v65, v18
	v_fmac_f32_e32 v20, v66, v19
	ds_read2_b32 v[18:19], v70 offset0:134 offset1:135
	s_waitcnt lgkmcnt(0)
	v_fmac_f32_e32 v20, v61, v18
	v_fmac_f32_e32 v20, v62, v19
	ds_read2_b32 v[18:19], v70 offset0:136 offset1:137
	s_waitcnt lgkmcnt(0)
	v_pk_mul_f32 v[18:19], v[8:9], v[18:19]
	s_nop 0
	v_add_f32_e32 v18, v20, v18
	v_add_f32_e32 v20, v18, v19
	ds_read2_b32 v[18:19], v70 offset0:138 offset1:139
	s_waitcnt lgkmcnt(0)
	v_pk_mul_f32 v[18:19], v[6:7], v[18:19]
	s_nop 0
	v_add_f32_e32 v18, v20, v18
	v_add_f32_e32 v20, v18, v19
	ds_read2_b32 v[18:19], v70 offset0:140 offset1:141
	s_waitcnt lgkmcnt(0)
	v_pk_mul_f32 v[18:19], v[4:5], v[18:19]
	s_nop 0
	v_add_f32_e32 v18, v20, v18
	v_add_f32_e32 v20, v18, v19
	ds_read2_b32 v[18:19], v70 offset0:142 offset1:143
	s_waitcnt lgkmcnt(0)
	v_pk_mul_f32 v[18:19], v[2:3], v[18:19]
	s_nop 0
	v_add_f32_e32 v18, v20, v18
	v_add_f32_e32 v18, v18, v19
	v_min_f32_e32 v19, 0, v18
	v_mul_f32_e64 v18, |v18|, s2
	v_exp_f32_e32 v18, v18
	s_nop 0
	v_add_f32_e32 v18, 1.0, v18
	v_cmp_gt_f32_e32 vcc, s23, v18
	s_nop 1
	v_cndmask_b32_e64 v20, 0, 32, vcc
	v_ldexp_f32 v18, v18, v20
	v_log_f32_e32 v18, v18
	s_nop 0
	v_mul_f32_e32 v20, 0x3f317217, v18
	v_fma_f32 v20, v18, s3, -v20
	v_fmac_f32_e32 v20, 0x3377d1cf, v18
	v_fmac_f32_e32 v20, 0x3f317217, v18
	v_cmp_lt_f32_e64 s[0:1], |v18|, s4
	s_nop 1
	v_cndmask_b32_e64 v18, v18, v20, s[0:1]
	v_cndmask_b32_e32 v20, 0, v176, vcc
	v_sub_f32_e32 v18, v18, v20
	v_sub_f32_e32 v20, v19, v18
	ds_read2_b32 v[18:19], v70 offset0:144 offset1:145
	s_waitcnt lgkmcnt(0)
; DI void gla_prep_item(const P& p, int l, int item, unsigned char* smem) {
;     ...
;     float cum[16]; float run = 0.f;
; #pragma unroll
;     for (int ii = 0; ii < 16; ++ii) {
;         const int i = 16 * half + ii; float z = bdv;
; #pragma unroll
;         for (int r = 0; r < 16; ++r) z += slr[i * 16 + r] * wd[r];
;         const float ls = fminf(z, 0.f) - __logf(1.f + __expf(-fabsf(z)));
;         run += ls * (1.f / 16.f); cum[ii] = run;
;     }
	v_fma_f32 v21, v67, v18, v69
	v_fmac_f32_e32 v21, v68, v19
	ds_read2_b32 v[18:19], v70 offset0:146 offset1:147
	s_waitcnt lgkmcnt(0)
	v_fmac_f32_e32 v21, v63, v18
	v_fmac_f32_e32 v21, v64, v19
	ds_read2_b32 v[18:19], v70 offset0:148 offset1:149
	s_waitcnt lgkmcnt(0)
	v_fmac_f32_e32 v21, v65, v18
	v_fmac_f32_e32 v21, v66, v19
	ds_read2_b32 v[18:19], v70 offset0:150 offset1:151
	s_waitcnt lgkmcnt(0)
	v_fmac_f32_e32 v21, v61, v18
	v_fmac_f32_e32 v21, v62, v19
	ds_read2_b32 v[18:19], v70 offset0:152 offset1:153
	s_waitcnt lgkmcnt(0)
	v_pk_mul_f32 v[18:19], v[8:9], v[18:19]
	s_nop 0
	v_add_f32_e32 v18, v21, v18
	v_add_f32_e32 v21, v18, v19
	ds_read2_b32 v[18:19], v70 offset0:154 offset1:155
	s_waitcnt lgkmcnt(0)
	v_pk_mul_f32 v[18:19], v[6:7], v[18:19]
	s_nop 0
	v_add_f32_e32 v18, v21, v18
	v_add_f32_e32 v21, v18, v19
	ds_read2_b32 v[18:19], v70 offset0:156 offset1:157
	s_waitcnt lgkmcnt(0)
	v_pk_mul_f32 v[18:19], v[4:5], v[18:19]
	s_nop 0
	v_add_f32_e32 v18, v21, v18
	v_add_f32_e32 v21, v18, v19
	ds_read2_b32 v[18:19], v70 offset0:158 offset1:159
	s_waitcnt lgkmcnt(0)
	v_pk_mul_f32 v[18:19], v[2:3], v[18:19]
	s_nop 0
	v_add_f32_e32 v18, v21, v18
	v_add_f32_e32 v18, v18, v19
	v_min_f32_e32 v19, 0, v18
	v_mul_f32_e64 v18, |v18|, s2
	v_exp_f32_e32 v18, v18
	s_nop 0
	v_add_f32_e32 v18, 1.0, v18
	v_cmp_gt_f32_e32 vcc, s23, v18
	s_nop 1
	v_cndmask_b32_e64 v21, 0, 32, vcc
	v_ldexp_f32 v18, v18, v21
	v_log_f32_e32 v18, v18
	s_nop 0
	v_mul_f32_e32 v21, 0x3f317217, v18
	v_fma_f32 v21, v18, s3, -v21
	v_fmac_f32_e32 v21, 0x3377d1cf, v18
	v_fmac_f32_e32 v21, 0x3f317217, v18
	v_cmp_lt_f32_e64 s[0:1], |v18|, s4
	s_nop 1
	v_cndmask_b32_e64 v18, v18, v21, s[0:1]
	v_cndmask_b32_e32 v21, 0, v176, vcc
	v_sub_f32_e32 v18, v18, v21
	v_sub_f32_e32 v19, v19, v18
	v_fmamk_f32 v18, v20, 0x3d800000, v17
	ds_read2_b32 v[20:21], v70 offset0:160 offset1:161
	v_fmamk_f32 v19, v19, 0x3d800000, v18
	s_waitcnt lgkmcnt(0)
	v_fma_f32 v22, v67, v20, v69
	v_fmac_f32_e32 v22, v68, v21
	ds_read2_b32 v[20:21], v70 offset0:162 offset1:163
	s_waitcnt lgkmcnt(0)
	v_fmac_f32_e32 v22, v63, v20
	v_fmac_f32_e32 v22, v64, v21
	ds_read2_b32 v[20:21], v70 offset0:164 offset1:165
	s_waitcnt lgkmcnt(0)
	v_fmac_f32_e32 v22, v65, v20
	v_fmac_f32_e32 v22, v66, v21
	ds_read2_b32 v[20:21], v70 offset0:166 offset1:167
	s_waitcnt lgkmcnt(0)
	v_fmac_f32_e32 v22, v61, v20
	v_fmac_f32_e32 v22, v62, v21
	ds_read2_b32 v[20:21], v70 offset0:168 offset1:169
	s_waitcnt lgkmcnt(0)
	v_pk_mul_f32 v[20:21], v[8:9], v[20:21]
	s_nop 0
	v_add_f32_e32 v20, v22, v20
	v_add_f32_e32 v22, v20, v21
	ds_read2_b32 v[20:21], v70 offset0:170 offset1:171
	s_waitcnt lgkmcnt(0)
	v_pk_mul_f32 v[20:21], v[6:7], v[20:21]
	s_nop 0
	v_add_f32_e32 v20, v22, v20
	v_add_f32_e32 v22, v20, v21
	ds_read2_b32 v[20:21], v70 offset0:172 offset1:173
	s_waitcnt lgkmcnt(0)
	v_pk_mul_f32 v[20:21], v[4:5], v[20:21]
	s_nop 0
	v_add_f32_e32 v20, v22, v20
	v_add_f32_e32 v22, v20, v21
	ds_read2_b32 v[20:21], v70 offset0:174 offset1:175
	s_waitcnt lgkmcnt(0)
	v_pk_mul_f32 v[20:21], v[2:3], v[20:21]
	s_nop 0
	v_add_f32_e32 v20, v22, v20
	v_add_f32_e32 v20, v20, v21
	v_min_f32_e32 v21, 0, v20
	v_mul_f32_e64 v20, |v20|, s2
	v_exp_f32_e32 v20, v20
	s_nop 0
	v_add_f32_e32 v20, 1.0, v20
	v_cmp_gt_f32_e32 vcc, s23, v20
	s_nop 1
	v_cndmask_b32_e64 v22, 0, 32, vcc
	v_ldexp_f32 v20, v20, v22
	v_log_f32_e32 v20, v20
	s_nop 0
	v_mul_f32_e32 v22, 0x3f317217, v20
	v_fma_f32 v22, v20, s3, -v22
	v_fmac_f32_e32 v22, 0x3377d1cf, v20
	v_fmac_f32_e32 v22, 0x3f317217, v20
	v_cmp_lt_f32_e64 s[0:1], |v20|, s4
	s_nop 1
	v_cndmask_b32_e64 v20, v20, v22, s[0:1]
	v_cndmask_b32_e32 v22, 0, v176, vcc
	v_sub_f32_e32 v20, v20, v22
	v_sub_f32_e32 v22, v21, v20
	ds_read2_b32 v[20:21], v70 offset0:176 offset1:177
	s_waitcnt lgkmcnt(0)
	v_fma_f32 v23, v67, v20, v69
	v_fmac_f32_e32 v23, v68, v21
	ds_read2_b32 v[20:21], v70 offset0:178 offset1:179
	s_waitcnt lgkmcnt(0)
	v_fmac_f32_e32 v23, v63, v20
	v_fmac_f32_e32 v23, v64, v21
	ds_read2_b32 v[20:21], v70 offset0:180 offset1:181
	s_waitcnt lgkmcnt(0)
	v_fmac_f32_e32 v23, v65, v20
	v_fmac_f32_e32 v23, v66, v21
	ds_read2_b32 v[20:21], v70 offset0:182 offset1:183
	s_waitcnt lgkmcnt(0)
	v_fmac_f32_e32 v23, v61, v20
	v_fmac_f32_e32 v23, v62, v21
	ds_read2_b32 v[20:21], v70 offset0:184 offset1:185
	s_waitcnt lgkmcnt(0)
	v_pk_mul_f32 v[20:21], v[8:9], v[20:21]
	s_nop 0
	v_add_f32_e32 v20, v23, v20
	v_add_f32_e32 v23, v20, v21
	ds_read2_b32 v[20:21], v70 offset0:186 offset1:187
	s_waitcnt lgkmcnt(0)
	v_pk_mul_f32 v[20:21], v[6:7], v[20:21]
	s_nop 0
	v_add_f32_e32 v20, v23, v20
	v_add_f32_e32 v23, v20, v21
	ds_read2_b32 v[20:21], v70 offset0:188 offset1:189
	s_waitcnt lgkmcnt(0)
	v_pk_mul_f32 v[20:21], v[4:5], v[20:21]
	s_nop 0
	v_add_f32_e32 v20, v23, v20
	v_add_f32_e32 v23, v20, v21
	ds_read2_b32 v[20:21], v70 offset0:190 offset1:191
	s_waitcnt lgkmcnt(0)
	v_pk_mul_f32 v[20:21], v[2:3], v[20:21]
	s_nop 0
	v_add_f32_e32 v20, v23, v20
	v_add_f32_e32 v20, v20, v21
	v_min_f32_e32 v21, 0, v20
	v_mul_f32_e64 v20, |v20|, s2
	v_exp_f32_e32 v20, v20
	s_nop 0
	v_add_f32_e32 v20, 1.0, v20
	v_cmp_gt_f32_e32 vcc, s23, v20
	s_nop 1
	v_cndmask_b32_e64 v23, 0, 32, vcc
	v_ldexp_f32 v20, v20, v23
	v_log_f32_e32 v20, v20
	s_nop 0
	v_mul_f32_e32 v23, 0x3f317217, v20
	v_fma_f32 v23, v20, s3, -v23
	v_fmac_f32_e32 v23, 0x3377d1cf, v20
	v_fmac_f32_e32 v23, 0x3f317217, v20
	v_cmp_lt_f32_e64 s[0:1], |v20|, s4
	s_nop 1
	v_cndmask_b32_e64 v20, v20, v23, s[0:1]
	v_cndmask_b32_e32 v23, 0, v176, vcc
	v_sub_f32_e32 v20, v20, v23
	v_sub_f32_e32 v21, v21, v20
	v_fmamk_f32 v20, v22, 0x3d800000, v19
	ds_read2_b32 v[22:23], v70 offset0:192 offset1:193
	v_fmamk_f32 v21, v21, 0x3d800000, v20
	s_waitcnt lgkmcnt(0)
; DI void gla_prep_item(const P& p, int l, int item, unsigned char* smem) {
;     ...
;     float cum[16]; float run = 0.f;
; #pragma unroll
;     for (int ii = 0; ii < 16; ++ii) {
;         const int i = 16 * half + ii; float z = bdv;
; #pragma unroll
;         for (int r = 0; r < 16; ++r) z += slr[i * 16 + r] * wd[r];
;         const float ls = fminf(z, 0.f) - __logf(1.f + __expf(-fabsf(z)));
;         run += ls * (1.f / 16.f); cum[ii] = run;
;     }
	v_fma_f32 v71, v67, v22, v69
	v_fmac_f32_e32 v71, v68, v23
	ds_read2_b32 v[22:23], v70 offset0:194 offset1:195
	s_waitcnt lgkmcnt(0)
	v_fmac_f32_e32 v71, v63, v22
	v_fmac_f32_e32 v71, v64, v23
	ds_read2_b32 v[22:23], v70 offset0:196 offset1:197
	s_waitcnt lgkmcnt(0)
	v_fmac_f32_e32 v71, v65, v22
	v_fmac_f32_e32 v71, v66, v23
	ds_read2_b32 v[22:23], v70 offset0:198 offset1:199
	s_waitcnt lgkmcnt(0)
	v_fmac_f32_e32 v71, v61, v22
	v_fmac_f32_e32 v71, v62, v23
	ds_read2_b32 v[22:23], v70 offset0:200 offset1:201
	s_waitcnt lgkmcnt(0)
	v_pk_mul_f32 v[22:23], v[8:9], v[22:23]
	s_nop 0
	v_add_f32_e32 v22, v71, v22
	v_add_f32_e32 v71, v22, v23
	ds_read2_b32 v[22:23], v70 offset0:202 offset1:203
	s_waitcnt lgkmcnt(0)
	v_pk_mul_f32 v[22:23], v[6:7], v[22:23]
	s_nop 0
	v_add_f32_e32 v22, v71, v22
	v_add_f32_e32 v71, v22, v23
	ds_read2_b32 v[22:23], v70 offset0:204 offset1:205
	s_waitcnt lgkmcnt(0)
	v_pk_mul_f32 v[22:23], v[4:5], v[22:23]
	s_nop 0
	v_add_f32_e32 v22, v71, v22
	v_add_f32_e32 v71, v22, v23
	ds_read2_b32 v[22:23], v70 offset0:206 offset1:207
	s_waitcnt lgkmcnt(0)
	v_pk_mul_f32 v[22:23], v[2:3], v[22:23]
	s_nop 0
	v_add_f32_e32 v22, v71, v22
	v_add_f32_e32 v22, v22, v23
	v_min_f32_e32 v23, 0, v22
	v_mul_f32_e64 v22, |v22|, s2
	v_exp_f32_e32 v22, v22
	s_nop 0
	v_add_f32_e32 v22, 1.0, v22
	v_cmp_gt_f32_e32 vcc, s23, v22
	s_nop 1
	v_cndmask_b32_e64 v71, 0, 32, vcc
	v_ldexp_f32 v22, v22, v71
	v_log_f32_e32 v22, v22
	s_nop 0
	v_mul_f32_e32 v71, 0x3f317217, v22
	v_fma_f32 v71, v22, s3, -v71
	v_fmac_f32_e32 v71, 0x3377d1cf, v22
	v_fmac_f32_e32 v71, 0x3f317217, v22
	v_cmp_lt_f32_e64 s[0:1], |v22|, s4
	s_nop 1
	v_cndmask_b32_e64 v22, v22, v71, s[0:1]
	v_cndmask_b32_e32 v71, 0, v176, vcc
	v_sub_f32_e32 v22, v22, v71
	v_sub_f32_e32 v71, v23, v22
	ds_read2_b32 v[22:23], v70 offset0:208 offset1:209
	s_waitcnt lgkmcnt(0)
	v_fma_f32 v72, v67, v22, v69
	v_fmac_f32_e32 v72, v68, v23
	ds_read2_b32 v[22:23], v70 offset0:210 offset1:211
	s_waitcnt lgkmcnt(0)
	v_fmac_f32_e32 v72, v63, v22
	v_fmac_f32_e32 v72, v64, v23
	ds_read2_b32 v[22:23], v70 offset0:212 offset1:213
	s_waitcnt lgkmcnt(0)
	v_fmac_f32_e32 v72, v65, v22
	v_fmac_f32_e32 v72, v66, v23
	ds_read2_b32 v[22:23], v70 offset0:214 offset1:215
	s_waitcnt lgkmcnt(0)
	v_fmac_f32_e32 v72, v61, v22
	v_fmac_f32_e32 v72, v62, v23
	ds_read2_b32 v[22:23], v70 offset0:216 offset1:217
	s_waitcnt lgkmcnt(0)
	v_pk_mul_f32 v[22:23], v[8:9], v[22:23]
	s_nop 0
	v_add_f32_e32 v22, v72, v22
	v_add_f32_e32 v72, v22, v23
	ds_read2_b32 v[22:23], v70 offset0:218 offset1:219
	s_waitcnt lgkmcnt(0)
	v_pk_mul_f32 v[22:23], v[6:7], v[22:23]
	s_nop 0
	v_add_f32_e32 v22, v72, v22
	v_add_f32_e32 v72, v22, v23
	ds_read2_b32 v[22:23], v70 offset0:220 offset1:221
	s_waitcnt lgkmcnt(0)
	v_pk_mul_f32 v[22:23], v[4:5], v[22:23]
	s_nop 0
	v_add_f32_e32 v22, v72, v22
	v_add_f32_e32 v72, v22, v23
	ds_read2_b32 v[22:23], v70 offset0:222 offset1:223
	s_waitcnt lgkmcnt(0)
	v_pk_mul_f32 v[22:23], v[2:3], v[22:23]
	s_nop 0
	v_add_f32_e32 v22, v72, v22
	v_add_f32_e32 v22, v22, v23
	v_min_f32_e32 v23, 0, v22
	v_mul_f32_e64 v22, |v22|, s2
	v_exp_f32_e32 v22, v22
	s_nop 0
	v_add_f32_e32 v22, 1.0, v22
	v_cmp_gt_f32_e32 vcc, s23, v22
	s_nop 1
	v_cndmask_b32_e64 v72, 0, 32, vcc
	v_ldexp_f32 v22, v22, v72
	v_log_f32_e32 v22, v22
	s_nop 0
	v_mul_f32_e32 v72, 0x3f317217, v22
	v_fma_f32 v72, v22, s3, -v72
	v_fmac_f32_e32 v72, 0x3377d1cf, v22
	v_fmac_f32_e32 v72, 0x3f317217, v22
	v_cmp_lt_f32_e64 s[0:1], |v22|, s4
	s_nop 1
	v_cndmask_b32_e64 v22, v22, v72, s[0:1]
	v_cndmask_b32_e32 v72, 0, v176, vcc
	v_sub_f32_e32 v22, v22, v72
	ds_read2_b32 v[72:73], v70 offset0:224 offset1:225
	v_sub_f32_e32 v23, v23, v22
	v_fmamk_f32 v22, v71, 0x3d800000, v21
	v_fmamk_f32 v23, v23, 0x3d800000, v22
	s_waitcnt lgkmcnt(0)
	v_fma_f32 v71, v67, v72, v69
	v_fmac_f32_e32 v71, v68, v73
	ds_read2_b32 v[72:73], v70 offset0:226 offset1:227
	s_waitcnt lgkmcnt(0)
	v_fmac_f32_e32 v71, v63, v72
	v_fmac_f32_e32 v71, v64, v73
	ds_read2_b32 v[72:73], v70 offset0:228 offset1:229
	s_waitcnt lgkmcnt(0)
	v_fmac_f32_e32 v71, v65, v72
	v_fmac_f32_e32 v71, v66, v73
	ds_read2_b32 v[72:73], v70 offset0:230 offset1:231
	s_waitcnt lgkmcnt(0)
; DI void gla_prep_item(const P& p, int l, int item, unsigned char* smem) {
;     ...
;     }
;     if (half == 0) stot[cch] = run;
;     __syncthreads();
;     if (half == 1) { const float t = stot[cch];
; #pragma unroll
;         for (int ii = 0; ii < 16; ++ii) cum[ii] += t;
;         slast[cch] = cum[15]; }
	v_fmac_f32_e32 v71, v61, v72
	v_fmac_f32_e32 v71, v62, v73
	ds_read2_b32 v[72:73], v70 offset0:232 offset1:233
	s_waitcnt lgkmcnt(0)
	v_pk_mul_f32 v[72:73], v[8:9], v[72:73]
	s_nop 0
	v_add_f32_e32 v71, v71, v72
	v_add_f32_e32 v71, v71, v73
	ds_read2_b32 v[72:73], v70 offset0:234 offset1:235
	s_waitcnt lgkmcnt(0)
	v_pk_mul_f32 v[72:73], v[6:7], v[72:73]
	s_nop 0
	v_add_f32_e32 v71, v71, v72
	v_add_f32_e32 v71, v71, v73
	ds_read2_b32 v[72:73], v70 offset0:236 offset1:237
	s_waitcnt lgkmcnt(0)
	v_pk_mul_f32 v[72:73], v[4:5], v[72:73]
	s_nop 0
	v_add_f32_e32 v71, v71, v72
	v_add_f32_e32 v71, v71, v73
	ds_read2_b32 v[72:73], v70 offset0:238 offset1:239
	s_waitcnt lgkmcnt(0)
	v_pk_mul_f32 v[72:73], v[2:3], v[72:73]
	s_nop 0
	v_add_f32_e32 v71, v71, v72
	v_add_f32_e32 v71, v71, v73
	v_min_f32_e32 v72, 0, v71
	v_mul_f32_e64 v71, |v71|, s2
	v_exp_f32_e32 v71, v71
	s_nop 0
	v_add_f32_e32 v71, 1.0, v71
	v_cmp_gt_f32_e32 vcc, s23, v71
	s_nop 1
	v_cndmask_b32_e64 v73, 0, 32, vcc
	v_ldexp_f32 v71, v71, v73
	v_log_f32_e32 v71, v71
	s_nop 0
	v_mul_f32_e32 v73, 0x3f317217, v71
	v_fma_f32 v73, v71, s3, -v73
	v_fmac_f32_e32 v73, 0x3377d1cf, v71
	v_fmac_f32_e32 v73, 0x3f317217, v71
	v_cmp_lt_f32_e64 s[0:1], |v71|, s4
	s_nop 1
	v_cndmask_b32_e64 v71, v71, v73, s[0:1]
	v_cndmask_b32_e32 v73, 0, v176, vcc
	v_sub_f32_e32 v71, v71, v73
	v_sub_f32_e32 v71, v72, v71
	ds_read2_b32 v[72:73], v70 offset0:240 offset1:241
	s_waitcnt lgkmcnt(0)
	v_fmac_f32_e32 v69, v67, v72
	v_fmac_f32_e32 v69, v68, v73
	ds_read2_b32 v[72:73], v70 offset0:242 offset1:243
	s_waitcnt lgkmcnt(0)
	v_fmac_f32_e32 v69, v63, v72
	v_fmac_f32_e32 v69, v64, v73
	ds_read2_b32 v[72:73], v70 offset0:244 offset1:245
	s_waitcnt lgkmcnt(0)
	v_fmac_f32_e32 v69, v65, v72
	ds_read2_b32 v[64:65], v70 offset0:246 offset1:247
	v_fmac_f32_e32 v69, v66, v73
	s_waitcnt lgkmcnt(0)
	v_fmac_f32_e32 v69, v61, v64
	v_fmac_f32_e32 v69, v62, v65
	ds_read2_b32 v[62:63], v70 offset0:248 offset1:249
	s_waitcnt lgkmcnt(0)
	v_pk_mul_f32 v[8:9], v[8:9], v[62:63]
	s_nop 0
	v_add_f32_e32 v8, v69, v8
	v_add_f32_e32 v61, v8, v9
	ds_read2_b32 v[8:9], v70 offset0:250 offset1:251
	s_waitcnt lgkmcnt(0)
	v_pk_mul_f32 v[6:7], v[6:7], v[8:9]
	s_nop 0
	v_add_f32_e32 v6, v61, v6
	v_add_f32_e32 v8, v6, v7
	ds_read2_b32 v[6:7], v70 offset0:252 offset1:253
	s_waitcnt lgkmcnt(0)
	v_pk_mul_f32 v[4:5], v[4:5], v[6:7]
	s_nop 0
	v_add_f32_e32 v4, v8, v4
	v_add_f32_e32 v6, v4, v5
	v_or_b32_e32 v5, 0x3fc, v43
	v_add_u32_e32 v5, s26, v5
	ds_read_b32 v4, v70 offset:1016
	ds_read_b32 v5, v5
	s_waitcnt lgkmcnt(0)
	v_pk_mul_f32 v[2:3], v[2:3], v[4:5]
	s_nop 0
	v_add_f32_e32 v2, v6, v2
	v_add_f32_e32 v2, v2, v3
	v_min_f32_e32 v3, 0, v2
	v_mul_f32_e64 v2, |v2|, s2
	v_exp_f32_e32 v2, v2
	v_lshl_add_u32 v5, v1, 2, s26
	v_add_f32_e32 v2, 1.0, v2
	v_cmp_gt_f32_e32 vcc, s23, v2
	s_nop 1
	v_cndmask_b32_e64 v4, 0, 32, vcc
	v_ldexp_f32 v2, v2, v4
	v_log_f32_e32 v2, v2
	s_nop 0
	v_mul_f32_e32 v4, 0x3f317217, v2
	v_fma_f32 v4, v2, s3, -v4
	v_fmac_f32_e32 v4, 0x3377d1cf, v2
	v_fmac_f32_e32 v4, 0x3f317217, v2
	v_cmp_lt_f32_e64 s[0:1], |v2|, s4
	s_nop 1
	v_cndmask_b32_e64 v2, v2, v4, s[0:1]
	v_cndmask_b32_e32 v4, 0, v176, vcc
	v_sub_f32_e32 v2, v2, v4
	v_sub_f32_e32 v3, v3, v2
	v_fmamk_f32 v2, v71, 0x3d800000, v23
	v_fmamk_f32 v3, v3, 0x3d800000, v2
	v_cmp_gt_u32_e32 vcc, s5, v24
	s_and_saveexec_b64 s[0:1], vcc
	ds_write_b32 v5, v3 offset:2048
	s_or_b64 exec, exec, s[0:1]
	s_lshl_b32 s2, s24, 4
	v_cmp_eq_u32_e64 s[0:1], 1, v37
	s_waitcnt lgkmcnt(0)
	s_barrier
	s_and_saveexec_b64 s[36:37], s[0:1]
	s_cbranch_execz .LBB0_262
	ds_read_b32 v4, v5 offset:2048
	s_waitcnt lgkmcnt(0)
	v_pk_add_f32 v[10:11], v[10:11], v[4:5] op_sel_hi:[1,0]
	v_pk_add_f32 v[12:13], v[12:13], v[4:5] op_sel_hi:[1,0]
	v_pk_add_f32 v[14:15], v[14:15], v[4:5] op_sel_hi:[1,0]
	v_pk_add_f32 v[16:17], v[16:17], v[4:5] op_sel_hi:[1,0]
	v_pk_add_f32 v[18:19], v[18:19], v[4:5] op_sel_hi:[1,0]
	v_pk_add_f32 v[20:21], v[20:21], v[4:5] op_sel_hi:[1,0]
	v_pk_add_f32 v[22:23], v[22:23], v[4:5] op_sel_hi:[1,0]
	v_pk_add_f32 v[2:3], v[2:3], v[4:5] op_sel_hi:[1,0]
	ds_write_b32 v5, v3 offset:3072
